# ss row-scale block DMA-staged into LDS during K-loop for FFN-up epilogue (hides global load latency)
# speedup vs baseline: 1.0082x; 1.0082x over previous
.LBB0_79:
	s_and_b64 s[6:7], s[6:7], exec
	v_readlane_b32 s6, v254, 37
	v_readlane_b32 s22, v254, 39
	v_bfe_u32 v20, v16, 4, 2
	v_readlane_b32 s7, v254, 38
	v_readlane_b32 s23, v254, 40
	v_and_b32_e32 v17, 15, v16
	v_lshlrev_b32_e32 v18, 4, v20
	v_lshlrev_b32_e32 v16, 2, v16
	s_cselect_b32 s7, s7, s23
	s_cselect_b32 s6, s6, s22
	s_mov_b64 s[98:99], s[6:7]
	v_lshl_or_b32 v199, s21, 6, v17
	v_lshl_or_b32 v17, v17, 6, v18
	s_lshl_b32 s1, s21, 13
	v_and_b32_e32 v16, 32, v16
	v_bitop3_b32 v21, v17, s1, v16 bitop3:0xde
	s_lshl_b32 s1, s20, 5
	s_and_b32 s1, s1, 0x60
	s_lshl_b32 s20, s1, 7
	s_add_i32 m0, s46, 0x18000
	v_lshl_add_u64 v[8:9], v[8:9], 0, s[12:13]
	v_bitop3_b32 v201, v17, s20, v16 bitop3:0xde
	s_waitcnt vmcnt(4)
	s_barrier
	global_load_lds_dwordx4 v[8:9], off
	v_lshl_add_u64 v[6:7], v[6:7], 0, s[12:13]
	s_add_i32 m0, s46, 0x1a000
	s_add_i32 s20, s46, 0x8000
	s_add_i32 s21, s46, 0xa000
	global_load_lds_dwordx4 v[6:7], off
	v_lshl_add_u64 v[4:5], v[4:5], 0, s[12:13]
	s_mov_b32 m0, s20
	s_add_u32 s22, s30, 0x40080
	global_load_lds_dwordx4 v[4:5], off
	v_lshl_add_u64 v[2:3], v[2:3], 0, s[12:13]
	s_mov_b32 m0, s21
	s_addc_u32 s23, s31, 0
	global_load_lds_dwordx4 v[2:3], off
	s_add_i32 m0, s46, 0x1c000
	v_lshl_add_u64 v[2:3], s[22:23], 0, v[0:1]
	global_load_lds_dwordx4 v[2:3], off
	v_lshl_add_u64 v[2:3], s[22:23], 0, v[154:155]
	s_add_i32 m0, s46, 0x1e000
	v_mov_b32_e32 v19, v1
	global_load_lds_dwordx4 v[2:3], off
	v_lshlrev_b32_e32 v2, 14, v14
	v_and_b32_e32 v2, 0xffff8000, v2
	v_lshl_add_u32 v2, v13, 11, v2
	v_and_b32_e32 v3, 1, v14
	v_lshl_or_b32 v2, v3, 6, v2
	v_lshl_add_u32 v178, v15, 1, v2
	v_lshlrev_b32_e32 v2, 14, v10
	v_and_b32_e32 v2, 0xffff8000, v2
	s_waitcnt vmcnt(6)
	v_lshl_add_u32 v2, v11, 11, v2
	v_and_b32_e32 v3, 1, v10
	v_lshl_add_u64 v[160:161], s[6:7], 0, v[18:19]
	v_lshl_or_b32 v2, v3, 6, v2
	v_readlane_b32 s6, v253, 4
	v_lshl_or_b32 v204, v20, 3, s1
	v_mov_b32_e32 v179, v1
	v_lshl_add_u32 v180, v12, 1, v2
	v_mov_b32_e32 v181, v1
	s_mov_b32 s54, 0
	v_add_u32_e32 v205, 0, v21
	v_readlane_b32 s34, v253, 0
	s_mov_b32 s55, s6
	s_barrier
	v_readlane_b32 s7, v253, 5

.LBB0_83:
	s_add_u32 s1, s28, 0xfffc0080
	s_addc_u32 s22, s29, -1
	s_add_i32 s23, 0, 0x10000
	v_add_u32_e32 v142, s23, v201
	ds_read_b128 v[130:133], v142
	ds_read_b128 v[134:137], v142 offset:1024
	ds_read_b128 v[138:141], v142 offset:2048
	ds_read_b128 v[142:145], v142 offset:3072
	s_cmp_eq_u32 s60, 12
	s_cselect_b32 s43, s27, s22
	s_cselect_b32 s42, s56, s1
	s_cselect_b32 s31, s7, s59
	s_cselect_b32 s30, s57, s58
	v_lshl_add_u64 v[176:177], s[28:29], 0, v[178:179]
	s_add_i32 m0, s46, 0xc000
	ds_read_b128 v[146:149], v205
	ds_read_b128 v[150:153], v205 offset:1024
	ds_read_b128 v[182:185], v205 offset:2048
	ds_read_b128 v[186:189], v205 offset:3072
	ds_read_b128 v[190:193], v205 offset:4096
	ds_read_b128 v[194:197], v205 offset:5120
	ds_read_b128 v[206:209], v205 offset:6144
	ds_read_b128 v[216:219], v205 offset:7168
	global_load_lds_dwordx4 v[176:177], off
	v_lshl_add_u64 v[176:177], s[28:29], 0, v[180:181]
	s_add_i32 m0, s46, 0xe000
	s_nop 0
	global_load_lds_dwordx4 v[176:177], off
	s_waitcnt lgkmcnt(8)
	s_barrier
	s_waitcnt lgkmcnt(0)
	s_setprio 1
	s_waitcnt lgkmcnt(0)
	v_mfma_f32_16x16x32_bf16 v[126:129], v[130:133], v[146:149], v[126:129]
	v_mfma_f32_16x16x32_bf16 v[118:121], v[138:141], v[146:149], v[118:121]
	v_mfma_f32_16x16x32_bf16 v[110:113], v[130:133], v[182:185], v[110:113]
	v_mfma_f32_16x16x32_bf16 v[102:105], v[138:141], v[182:185], v[102:105]
	v_mfma_f32_16x16x32_bf16 v[94:97], v[130:133], v[190:193], v[94:97]
	v_mfma_f32_16x16x32_bf16 v[86:89], v[138:141], v[190:193], v[86:89]
	v_mfma_f32_16x16x32_bf16 v[78:81], v[130:133], v[206:209], v[78:81]
	v_mfma_f32_16x16x32_bf16 v[70:73], v[138:141], v[206:209], v[70:73]
	v_mfma_f32_16x16x32_bf16 v[126:129], v[134:137], v[150:153], v[126:129]
	v_mfma_f32_16x16x32_bf16 v[118:121], v[142:145], v[150:153], v[118:121]
	v_mfma_f32_16x16x32_bf16 v[110:113], v[134:137], v[186:189], v[110:113]
	v_mfma_f32_16x16x32_bf16 v[102:105], v[142:145], v[186:189], v[102:105]
	v_mfma_f32_16x16x32_bf16 v[94:97], v[134:137], v[194:197], v[94:97]
	v_mfma_f32_16x16x32_bf16 v[86:89], v[142:145], v[194:197], v[86:89]
	v_mfma_f32_16x16x32_bf16 v[78:81], v[134:137], v[216:219], v[78:81]
	v_mfma_f32_16x16x32_bf16 v[70:73], v[142:145], v[216:219], v[70:73]
	s_setprio 0
	s_barrier
	s_add_i32 s1, 0, 0x14000
	s_add_i32 s22, s23, s17
	v_add_u32_e32 v168, s1, v201
	v_lshl_add_u64 v[176:177], s[30:31], 0, v[0:1]
	s_mov_b32 m0, s22
	ds_read_b128 v[230:233], v168
	ds_read_b128 v[234:237], v168 offset:1024
	ds_read_b128 v[238:241], v168 offset:2048
	ds_read_b128 v[242:245], v168 offset:3072
	global_load_lds_dwordx4 v[176:177], off
	v_lshl_add_u64 v[202:203], s[30:31], 0, v[154:155]
	s_add_i32 m0, s22, 0x2000
	s_nop 0
	global_load_lds_dwordx4 v[202:203], off
	s_barrier
	s_waitcnt lgkmcnt(0)
	s_setprio 1
	s_waitcnt lgkmcnt(0)
	v_mfma_f32_16x16x32_bf16 v[122:125], v[230:233], v[146:149], v[122:125]
	v_mfma_f32_16x16x32_bf16 v[114:117], v[238:241], v[146:149], v[114:117]
	v_mfma_f32_16x16x32_bf16 v[106:109], v[230:233], v[182:185], v[106:109]
	v_mfma_f32_16x16x32_bf16 v[98:101], v[238:241], v[182:185], v[98:101]
	v_mfma_f32_16x16x32_bf16 v[90:93], v[230:233], v[190:193], v[90:93]
	v_mfma_f32_16x16x32_bf16 v[82:85], v[238:241], v[190:193], v[82:85]
	v_mfma_f32_16x16x32_bf16 v[74:77], v[230:233], v[206:209], v[74:77]
	v_mfma_f32_16x16x32_bf16 v[66:69], v[238:241], v[206:209], v[66:69]
	v_mfma_f32_16x16x32_bf16 v[122:125], v[234:237], v[150:153], v[122:125]
	v_mfma_f32_16x16x32_bf16 v[114:117], v[242:245], v[150:153], v[114:117]
	v_mfma_f32_16x16x32_bf16 v[106:109], v[234:237], v[186:189], v[106:109]
	v_mfma_f32_16x16x32_bf16 v[98:101], v[242:245], v[186:189], v[98:101]
	v_mfma_f32_16x16x32_bf16 v[90:93], v[234:237], v[194:197], v[90:93]
	v_mfma_f32_16x16x32_bf16 v[82:85], v[242:245], v[194:197], v[82:85]
	v_mfma_f32_16x16x32_bf16 v[74:77], v[234:237], v[216:219], v[74:77]
	v_mfma_f32_16x16x32_bf16 v[66:69], v[242:245], v[216:219], v[66:69]
	s_setprio 0
	s_mov_b32 m0, s46
	v_lshl_add_u64 v[220:221], s[42:43], 0, v[158:159]
	s_barrier
	ds_read_b128 v[146:149], v205 offset:16384
	ds_read_b128 v[150:153], v205 offset:17408
	ds_read_b128 v[182:185], v205 offset:18432
	ds_read_b128 v[186:189], v205 offset:19456
	ds_read_b128 v[190:193], v205 offset:20480
	ds_read_b128 v[194:197], v205 offset:21504
	ds_read_b128 v[206:209], v205 offset:22528
	ds_read_b128 v[216:219], v205 offset:23552
	global_load_lds_dwordx4 v[220:221], off
	v_lshl_add_u64 v[246:247], s[42:43], 0, v[156:157]
	s_mov_b32 m0, s47
	s_nop 0
	global_load_lds_dwordx4 v[246:247], off
	s_barrier
	s_waitcnt lgkmcnt(0)
	s_setprio 1
	s_waitcnt lgkmcnt(0)
	v_mfma_f32_16x16x32_bf16 v[62:65], v[130:133], v[146:149], v[62:65]
	v_mfma_f32_16x16x32_bf16 v[54:57], v[138:141], v[146:149], v[54:57]
	v_mfma_f32_16x16x32_bf16 v[46:49], v[130:133], v[182:185], v[46:49]
	v_mfma_f32_16x16x32_bf16 v[38:41], v[138:141], v[182:185], v[38:41]
	v_mfma_f32_16x16x32_bf16 v[30:33], v[130:133], v[190:193], v[30:33]
	v_mfma_f32_16x16x32_bf16 v[22:25], v[138:141], v[190:193], v[22:25]
	v_mfma_f32_16x16x32_bf16 v[14:17], v[130:133], v[206:209], v[14:17]
	v_mfma_f32_16x16x32_bf16 v[6:9], v[138:141], v[206:209], v[6:9]
	v_mfma_f32_16x16x32_bf16 v[62:65], v[134:137], v[150:153], v[62:65]
	v_mfma_f32_16x16x32_bf16 v[54:57], v[142:145], v[150:153], v[54:57]
	v_mfma_f32_16x16x32_bf16 v[46:49], v[134:137], v[186:189], v[46:49]
	v_mfma_f32_16x16x32_bf16 v[38:41], v[142:145], v[186:189], v[38:41]
	v_mfma_f32_16x16x32_bf16 v[30:33], v[134:137], v[194:197], v[30:33]
	v_mfma_f32_16x16x32_bf16 v[22:25], v[142:145], v[194:197], v[22:25]
	v_mfma_f32_16x16x32_bf16 v[14:17], v[134:137], v[216:219], v[14:17]
	v_mfma_f32_16x16x32_bf16 v[6:9], v[142:145], v[216:219], v[6:9]
	s_setprio 0
	s_barrier
	s_add_u32 s22, s30, 0x40000
	s_addc_u32 s23, s31, 0
	s_add_i32 s1, s1, s17
	v_lshl_add_u64 v[130:131], s[22:23], 0, v[0:1]
	s_mov_b32 m0, s1
	s_nop 0
	global_load_lds_dwordx4 v[130:131], off
	v_lshl_add_u64 v[130:131], s[22:23], 0, v[154:155]
	s_add_i32 m0, s1, 0x2000
	s_nop 0
	global_load_lds_dwordx4 v[130:131], off
	s_waitcnt vmcnt(6)
	s_barrier
	s_cmp_lg_u32 s60, -2
	s_cbranch_scc1 .Lssdma2_skip
	s_lshl_b32 s100, s55, 14
	s_add_u32 s100, s98, s100
	s_addc_u32 s101, s99, 0
	v_lshlrev_b32_e32 v248, 4, v167
	s_lshl_b32 m0, s46, 1
	v_add_u32_e32 v248, s46, v248
	s_add_i32 m0, m0, 0x20000
	s_nop 0
	global_load_lds_dwordx4 v248, s[100:101]
	global_load_lds_dwordx4 v248, s[100:101] offset:1024
.Lssdma2_skip:
	s_setprio 1
	v_mfma_f32_16x16x32_bf16 v[58:61], v[230:233], v[146:149], v[58:61]
	v_mfma_f32_16x16x32_bf16 v[50:53], v[238:241], v[146:149], v[50:53]
	v_mfma_f32_16x16x32_bf16 v[42:45], v[230:233], v[182:185], v[42:45]
	v_mfma_f32_16x16x32_bf16 v[34:37], v[238:241], v[182:185], v[34:37]
	v_mfma_f32_16x16x32_bf16 v[26:29], v[230:233], v[190:193], v[26:29]
	v_mfma_f32_16x16x32_bf16 v[18:21], v[238:241], v[190:193], v[18:21]
	v_mfma_f32_16x16x32_bf16 v[10:13], v[230:233], v[206:209], v[10:13]
	v_mfma_f32_16x16x32_bf16 v[2:5], v[238:241], v[206:209], v[2:5]
	v_mfma_f32_16x16x32_bf16 v[58:61], v[234:237], v[150:153], v[58:61]
	v_mfma_f32_16x16x32_bf16 v[50:53], v[242:245], v[150:153], v[50:53]
	v_mfma_f32_16x16x32_bf16 v[42:45], v[234:237], v[186:189], v[42:45]
	v_mfma_f32_16x16x32_bf16 v[34:37], v[242:245], v[186:189], v[34:37]
	v_mfma_f32_16x16x32_bf16 v[26:29], v[234:237], v[194:197], v[26:29]
	v_mfma_f32_16x16x32_bf16 v[18:21], v[242:245], v[194:197], v[18:21]
	v_mfma_f32_16x16x32_bf16 v[10:13], v[234:237], v[216:219], v[10:13]
	v_mfma_f32_16x16x32_bf16 v[2:5], v[242:245], v[216:219], v[2:5]
	s_setprio 0
	s_add_i32 s1, 0, 0x18000
	v_add_u32_e32 v142, s1, v201
	s_barrier
	ds_read_b128 v[130:133], v142
	ds_read_b128 v[134:137], v142 offset:1024
	ds_read_b128 v[138:141], v142 offset:2048
	ds_read_b128 v[142:145], v142 offset:3072
	s_add_u32 s22, s42, 0x40000
	s_addc_u32 s23, s43, 0
	s_mov_b32 m0, s48
	v_lshl_add_u64 v[230:231], s[22:23], 0, v[158:159]
	ds_read_b128 v[146:149], v205 offset:32768
	ds_read_b128 v[150:153], v205 offset:33792
	ds_read_b128 v[182:185], v205 offset:34816
	ds_read_b128 v[186:189], v205 offset:35840
	ds_read_b128 v[190:193], v205 offset:36864
	ds_read_b128 v[194:197], v205 offset:37888
	ds_read_b128 v[206:209], v205 offset:38912
	ds_read_b128 v[216:219], v205 offset:39936
	global_load_lds_dwordx4 v[230:231], off
	v_lshl_add_u64 v[230:231], s[22:23], 0, v[156:157]
	s_mov_b32 m0, s49
	s_nop 0
	global_load_lds_dwordx4 v[230:231], off
	s_waitcnt lgkmcnt(8)
	s_barrier
	s_waitcnt lgkmcnt(0)
	s_setprio 1
	s_waitcnt lgkmcnt(0)
	v_mfma_f32_16x16x32_bf16 v[126:129], v[130:133], v[146:149], v[126:129]
	v_mfma_f32_16x16x32_bf16 v[118:121], v[138:141], v[146:149], v[118:121]
	v_mfma_f32_16x16x32_bf16 v[110:113], v[130:133], v[182:185], v[110:113]
	v_mfma_f32_16x16x32_bf16 v[102:105], v[138:141], v[182:185], v[102:105]
	v_mfma_f32_16x16x32_bf16 v[94:97], v[130:133], v[190:193], v[94:97]
	v_mfma_f32_16x16x32_bf16 v[86:89], v[138:141], v[190:193], v[86:89]
	v_mfma_f32_16x16x32_bf16 v[78:81], v[130:133], v[206:209], v[78:81]
	v_mfma_f32_16x16x32_bf16 v[70:73], v[138:141], v[206:209], v[70:73]
	v_mfma_f32_16x16x32_bf16 v[126:129], v[134:137], v[150:153], v[126:129]
	v_mfma_f32_16x16x32_bf16 v[118:121], v[142:145], v[150:153], v[118:121]
	v_mfma_f32_16x16x32_bf16 v[110:113], v[134:137], v[186:189], v[110:113]
	v_mfma_f32_16x16x32_bf16 v[102:105], v[142:145], v[186:189], v[102:105]
	v_mfma_f32_16x16x32_bf16 v[94:97], v[134:137], v[194:197], v[94:97]
	v_mfma_f32_16x16x32_bf16 v[86:89], v[142:145], v[194:197], v[86:89]
	v_mfma_f32_16x16x32_bf16 v[78:81], v[134:137], v[216:219], v[78:81]
	v_mfma_f32_16x16x32_bf16 v[70:73], v[142:145], v[216:219], v[70:73]
	s_setprio 0
	s_barrier
	s_add_i32 s33, 0, 0x1c000
	s_add_i32 s1, s1, s17
	v_add_u32_e32 v168, s33, v201
	v_lshl_add_u64 v[176:177], v[176:177], 0, s[12:13]
	s_mov_b32 m0, s1
	ds_read_b128 v[230:233], v168
	ds_read_b128 v[234:237], v168 offset:1024
	ds_read_b128 v[238:241], v168 offset:2048
	ds_read_b128 v[242:245], v168 offset:3072
	global_load_lds_dwordx4 v[176:177], off
	v_lshl_add_u64 v[176:177], v[202:203], 0, s[12:13]
	s_add_i32 m0, s1, 0x2000
	s_nop 0
	global_load_lds_dwordx4 v[176:177], off
	s_barrier
	s_waitcnt lgkmcnt(0)
	s_setprio 1
	s_waitcnt lgkmcnt(0)
	v_mfma_f32_16x16x32_bf16 v[122:125], v[230:233], v[146:149], v[122:125]
	v_mfma_f32_16x16x32_bf16 v[114:117], v[238:241], v[146:149], v[114:117]
	v_mfma_f32_16x16x32_bf16 v[106:109], v[230:233], v[182:185], v[106:109]
	v_mfma_f32_16x16x32_bf16 v[98:101], v[238:241], v[182:185], v[98:101]
	v_mfma_f32_16x16x32_bf16 v[90:93], v[230:233], v[190:193], v[90:93]
	v_mfma_f32_16x16x32_bf16 v[82:85], v[238:241], v[190:193], v[82:85]
	v_mfma_f32_16x16x32_bf16 v[74:77], v[230:233], v[206:209], v[74:77]
	v_mfma_f32_16x16x32_bf16 v[66:69], v[238:241], v[206:209], v[66:69]
	v_mfma_f32_16x16x32_bf16 v[122:125], v[234:237], v[150:153], v[122:125]
	v_mfma_f32_16x16x32_bf16 v[114:117], v[242:245], v[150:153], v[114:117]
	v_mfma_f32_16x16x32_bf16 v[106:109], v[234:237], v[186:189], v[106:109]
	v_mfma_f32_16x16x32_bf16 v[98:101], v[242:245], v[186:189], v[98:101]
	v_mfma_f32_16x16x32_bf16 v[90:93], v[234:237], v[194:197], v[90:93]
	v_mfma_f32_16x16x32_bf16 v[82:85], v[242:245], v[194:197], v[82:85]
	v_mfma_f32_16x16x32_bf16 v[74:77], v[234:237], v[216:219], v[74:77]
	v_mfma_f32_16x16x32_bf16 v[66:69], v[242:245], v[216:219], v[66:69]
	s_setprio 0
	s_mov_b32 m0, s20
	v_lshl_add_u64 v[176:177], v[220:221], 0, s[12:13]
	s_barrier
	ds_read_b128 v[146:149], v205 offset:49152
	ds_read_b128 v[150:153], v205 offset:50176
	ds_read_b128 v[182:185], v205 offset:51200
	ds_read_b128 v[186:189], v205 offset:52224
	ds_read_b128 v[190:193], v205 offset:53248
	ds_read_b128 v[194:197], v205 offset:54272
	ds_read_b128 v[206:209], v205 offset:55296
	ds_read_b128 v[216:219], v205 offset:56320
	global_load_lds_dwordx4 v[176:177], off
	v_lshl_add_u64 v[176:177], v[246:247], 0, s[12:13]
	s_mov_b32 m0, s21
	s_nop 0
	global_load_lds_dwordx4 v[176:177], off
	s_barrier
	s_waitcnt lgkmcnt(0)
	s_setprio 1
	s_waitcnt lgkmcnt(0)
	v_mfma_f32_16x16x32_bf16 v[62:65], v[130:133], v[146:149], v[62:65]
	v_mfma_f32_16x16x32_bf16 v[54:57], v[138:141], v[146:149], v[54:57]
	v_mfma_f32_16x16x32_bf16 v[46:49], v[130:133], v[182:185], v[46:49]
	v_mfma_f32_16x16x32_bf16 v[38:41], v[138:141], v[182:185], v[38:41]
	v_mfma_f32_16x16x32_bf16 v[30:33], v[130:133], v[190:193], v[30:33]
	v_mfma_f32_16x16x32_bf16 v[22:25], v[138:141], v[190:193], v[22:25]
	v_mfma_f32_16x16x32_bf16 v[14:17], v[130:133], v[206:209], v[14:17]
	v_mfma_f32_16x16x32_bf16 v[6:9], v[138:141], v[206:209], v[6:9]
	v_mfma_f32_16x16x32_bf16 v[62:65], v[134:137], v[150:153], v[62:65]
	v_mfma_f32_16x16x32_bf16 v[54:57], v[142:145], v[150:153], v[54:57]
	v_mfma_f32_16x16x32_bf16 v[46:49], v[134:137], v[186:189], v[46:49]
	v_mfma_f32_16x16x32_bf16 v[38:41], v[142:145], v[186:189], v[38:41]
	v_mfma_f32_16x16x32_bf16 v[30:33], v[134:137], v[194:197], v[30:33]
	v_mfma_f32_16x16x32_bf16 v[22:25], v[142:145], v[194:197], v[22:25]
	v_mfma_f32_16x16x32_bf16 v[14:17], v[134:137], v[216:219], v[14:17]
	v_mfma_f32_16x16x32_bf16 v[6:9], v[142:145], v[216:219], v[6:9]
	s_setprio 0
	s_barrier
	s_add_u32 s22, s30, 0x40080
	s_addc_u32 s23, s31, 0
	s_add_i32 s1, s33, s17
	v_lshl_add_u64 v[130:131], s[22:23], 0, v[0:1]
	s_mov_b32 m0, s1
	s_nop 0
	global_load_lds_dwordx4 v[130:131], off
	v_lshl_add_u64 v[130:131], s[22:23], 0, v[154:155]
	s_add_i32 m0, s1, 0x2000
	s_nop 0
	global_load_lds_dwordx4 v[130:131], off
	s_waitcnt vmcnt(6)
	s_barrier
	s_setprio 1
	v_mfma_f32_16x16x32_bf16 v[58:61], v[230:233], v[146:149], v[58:61]
	v_mfma_f32_16x16x32_bf16 v[50:53], v[238:241], v[146:149], v[50:53]
	v_mfma_f32_16x16x32_bf16 v[42:45], v[230:233], v[182:185], v[42:45]
	v_mfma_f32_16x16x32_bf16 v[34:37], v[238:241], v[182:185], v[34:37]
	v_mfma_f32_16x16x32_bf16 v[26:29], v[230:233], v[190:193], v[26:29]
	v_mfma_f32_16x16x32_bf16 v[18:21], v[238:241], v[190:193], v[18:21]
	v_mfma_f32_16x16x32_bf16 v[10:13], v[230:233], v[206:209], v[10:13]
	v_mfma_f32_16x16x32_bf16 v[2:5], v[238:241], v[206:209], v[2:5]
	v_mfma_f32_16x16x32_bf16 v[58:61], v[234:237], v[150:153], v[58:61]
	v_mfma_f32_16x16x32_bf16 v[50:53], v[242:245], v[150:153], v[50:53]
	v_mfma_f32_16x16x32_bf16 v[42:45], v[234:237], v[186:189], v[42:45]
	v_mfma_f32_16x16x32_bf16 v[34:37], v[242:245], v[186:189], v[34:37]
	v_mfma_f32_16x16x32_bf16 v[26:29], v[234:237], v[194:197], v[26:29]
	v_mfma_f32_16x16x32_bf16 v[18:21], v[242:245], v[194:197], v[18:21]
	v_mfma_f32_16x16x32_bf16 v[10:13], v[234:237], v[216:219], v[10:13]
	v_mfma_f32_16x16x32_bf16 v[2:5], v[242:245], v[216:219], v[2:5]
	s_setprio 0
	s_add_i32 s60, s60, 2
	s_add_u32 s28, s28, 0x100
	s_addc_u32 s29, s29, 0
	s_add_u32 s58, s58, 0x100
	s_addc_u32 s59, s59, 0
	s_cmp_gt_u32 s60, 13
	s_barrier
	s_cbranch_scc0 .LBB0_83
	v_and_b32_e32 v249, 48, v212
	v_lshl_add_u32 v249, v199, 6, v249
	v_add_u32_e32 v249, 0x20000, v249
	v_lshl_add_u32 v196, s55, 8, v199
	v_ashrrev_i32_e32 v197, 31, v196
	v_lshlrev_b64 v[130:131], 6, v[196:197]
	v_or_b32_e32 v194, 16, v196
	v_lshl_add_u64 v[130:131], v[160:161], 0, v[130:131]
	v_ashrrev_i32_e32 v195, 31, v194
	ds_read_b128 v[206:209], v249
	v_lshlrev_b64 v[130:131], 6, v[194:195]
	v_lshl_add_u64 v[130:131], v[160:161], 0, v[130:131]
	ds_read_b128 v[216:219], v249 offset:1024
	v_or_b32_e32 v192, 32, v196
	v_ashrrev_i32_e32 v193, 31, v192
	v_lshlrev_b64 v[130:131], 6, v[192:193]
	v_or_b32_e32 v190, 48, v196
	v_lshl_add_u64 v[130:131], v[160:161], 0, v[130:131]
	v_ashrrev_i32_e32 v191, 31, v190
	ds_read_b128 v[150:153], v249 offset:2048
	v_lshlrev_b64 v[130:131], 6, v[190:191]
	v_lshl_add_u64 v[130:131], v[160:161], 0, v[130:131]
	ds_read_b128 v[146:149], v249 offset:3072
	v_add_u32_e32 v188, 0x80, v196
	v_ashrrev_i32_e32 v189, 31, v188
	v_lshlrev_b64 v[130:131], 6, v[188:189]
	v_add_u32_e32 v186, 0x90, v196
	v_lshl_add_u64 v[130:131], v[160:161], 0, v[130:131]
	v_ashrrev_i32_e32 v187, 31, v186
	ds_read_b128 v[142:145], v249 offset:8192
	v_lshlrev_b64 v[130:131], 6, v[186:187]
	v_lshl_add_u64 v[130:131], v[160:161], 0, v[130:131]
	ds_read_b128 v[138:141], v249 offset:9216
	v_add_u32_e32 v184, 0xa0, v196
	v_ashrrev_i32_e32 v185, 31, v184
	v_lshlrev_b64 v[130:131], 6, v[184:185]
	v_add_u32_e32 v182, 0xb0, v196
	v_lshl_add_u64 v[130:131], v[160:161], 0, v[130:131]
	v_ashrrev_i32_e32 v183, 31, v182
	ds_read_b128 v[134:137], v249 offset:10240
	v_lshlrev_b64 v[130:131], 6, v[182:183]
	v_lshl_add_u64 v[130:131], v[160:161], 0, v[130:131]
	ds_read_b128 v[130:133], v249 offset:11264
	v_and_b32_e32 v169, 64, v212
	v_xor_b32_e32 v168, 16, v212
	v_add_u32_e32 v169, 64, v169
	v_cmp_lt_i32_e32 vcc, v168, v169
	s_mov_b32 s22, 0x358637bd
	s_mov_b32 s55, s26
	v_cndmask_b32_e32 v168, v212, v168, vcc
	v_lshlrev_b32_e32 v185, 2, v168
	v_xor_b32_e32 v168, 32, v212
	v_cmp_lt_i32_e32 vcc, v168, v169
	s_mov_b64 s[30:31], s[44:45]
	s_mov_b64 s[28:29], s[36:37]
	v_cndmask_b32_e32 v168, v212, v168, vcc
	v_lshlrev_b32_e32 v183, 2, v168
	s_waitcnt lgkmcnt(0)
	v_mov_b32_e32 v176, v207
	v_mov_b32_e32 v177, v208
	v_mov_b32_e32 v207, v209
	v_mov_b32_e32 v202, v217
	v_mov_b32_e32 v203, v218
	v_mov_b32_e32 v217, v219
	v_pk_add_f32 v[176:177], v[176:177], v[206:207]
	v_pk_add_f32 v[202:203], v[202:203], v[216:217]
	v_mov_b32_e32 v207, v176
	v_mov_b32_e32 v206, v202
	v_mov_b32_e32 v176, v203
	v_pk_add_f32 v[176:177], v[206:207], v[176:177]
	ds_bpermute_b32 v203, v185, v177
	ds_bpermute_b32 v202, v185, v176
	s_waitcnt lgkmcnt(0)
	v_pk_add_f32 v[176:177], v[176:177], v[202:203]
	ds_bpermute_b32 v203, v183, v177
	ds_bpermute_b32 v202, v183, v176
	s_waitcnt lgkmcnt(0)
	v_pk_add_f32 v[176:177], v[176:177], v[202:203]
	v_mov_b64_e32 v[202:203], s[22:23]
	s_mov_b32 s22, 0x3a800000
	v_pk_fma_f32 v[176:177], v[176:177], s[22:23], v[202:203] op_sel_hi:[1,0,0]
	s_nop 0
	v_mul_f32_e32 v168, 0x4b800000, v177
	v_cmp_gt_f32_e64 s[42:43], s39, v177
	v_cmp_gt_f32_e32 vcc, s39, v176
	s_nop 0
	v_cndmask_b32_e64 v168, v177, v168, s[42:43]
	v_rsq_f32_e32 v168, v168
	v_mov_b32_e32 v177, v152
	v_mov_b32_e32 v152, v147
	v_mov_b32_e32 v147, v149
	v_mul_f32_e32 v169, 0x45800000, v168
	v_cndmask_b32_e64 v200, v168, v169, s[42:43]
	v_mul_f32_e32 v168, 0x4b800000, v176
	v_cndmask_b32_e32 v168, v176, v168, vcc
	v_mov_b32_e32 v176, v151
	v_mov_b32_e32 v151, v153
	v_mov_b32_e32 v153, v148
	v_pk_add_f32 v[150:151], v[176:177], v[150:151]
	v_pk_add_f32 v[146:147], v[152:153], v[146:147]
	v_mov_b32_e32 v149, v150
	v_mov_b32_e32 v148, v146
	v_mov_b32_e32 v150, v147
	v_pk_add_f32 v[146:147], v[148:149], v[150:151]
	ds_bpermute_b32 v149, v185, v147
	ds_bpermute_b32 v148, v185, v146
	v_mov_b32_e32 v150, v143
	v_mov_b32_e32 v151, v144
	v_mov_b32_e32 v143, v145
	v_mov_b32_e32 v144, v139
	v_mov_b32_e32 v145, v140
	v_mov_b32_e32 v139, v141
	v_pk_add_f32 v[142:143], v[150:151], v[142:143]
	v_pk_add_f32 v[138:139], v[144:145], v[138:139]
	s_waitcnt lgkmcnt(0)
	v_pk_add_f32 v[146:147], v[146:147], v[148:149]
	v_mov_b32_e32 v140, v138
	v_mov_b32_e32 v141, v142
	v_mov_b32_e32 v142, v139
	ds_bpermute_b32 v149, v183, v147
	ds_bpermute_b32 v148, v183, v146
	v_pk_add_f32 v[138:139], v[140:141], v[142:143]
	ds_bpermute_b32 v141, v185, v139
	ds_bpermute_b32 v140, v185, v138
	v_mov_b32_e32 v142, v135
	v_mov_b32_e32 v143, v136
	v_mov_b32_e32 v135, v137
	v_mov_b32_e32 v136, v131
	v_mov_b32_e32 v137, v132
	v_mov_b32_e32 v131, v133
	s_waitcnt lgkmcnt(2)
	v_pk_add_f32 v[146:147], v[146:147], v[148:149]
	v_pk_add_f32 v[134:135], v[142:143], v[134:135]
	v_pk_add_f32 v[130:131], v[136:137], v[130:131]
	v_pk_fma_f32 v[146:147], v[146:147], s[22:23], v[202:203] op_sel_hi:[1,0,0]
	s_waitcnt lgkmcnt(0)
	v_pk_add_f32 v[138:139], v[138:139], v[140:141]
	v_mov_b32_e32 v132, v130
	v_mov_b32_e32 v133, v134
	v_mov_b32_e32 v134, v131
	v_mul_f32_e32 v148, 0x4b800000, v147
	v_cmp_gt_f32_e64 s[42:43], s39, v147
	ds_bpermute_b32 v141, v183, v139
	ds_bpermute_b32 v140, v183, v138
	v_pk_add_f32 v[130:131], v[132:133], v[134:135]
	v_cndmask_b32_e64 v147, v147, v148, s[42:43]
	ds_bpermute_b32 v133, v185, v131
	ds_bpermute_b32 v132, v185, v130
	v_rsq_f32_e32 v168, v168
	v_rsq_f32_e32 v147, v147
	s_waitcnt lgkmcnt(2)
	v_pk_add_f32 v[138:139], v[138:139], v[140:141]
	v_pk_mul_f32 v[126:127], v[126:127], v[200:201] op_sel_hi:[1,0]
	v_mul_f32_e32 v169, 0x45800000, v168
	v_mul_f32_e32 v148, 0x45800000, v147
	v_pk_fma_f32 v[138:139], v[138:139], s[22:23], v[202:203] op_sel_hi:[1,0,0]
	s_waitcnt lgkmcnt(0)
	v_pk_add_f32 v[130:131], v[130:131], v[132:133]
	v_cndmask_b32_e32 v198, v168, v169, vcc
	v_cmp_gt_f32_e32 vcc, s39, v146
	v_cndmask_b32_e64 v148, v147, v148, s[42:43]
	v_mul_f32_e32 v147, 0x4b800000, v146
	v_mul_f32_e32 v140, 0x4b800000, v139
	v_cmp_gt_f32_e64 s[42:43], s39, v139
	ds_bpermute_b32 v133, v183, v131
	ds_bpermute_b32 v132, v183, v130
	v_cndmask_b32_e32 v146, v146, v147, vcc
	v_cndmask_b32_e64 v139, v139, v140, s[42:43]
	v_rsq_f32_e32 v146, v146
	v_rsq_f32_e32 v139, v139
	s_waitcnt lgkmcnt(0)
	v_pk_add_f32 v[130:131], v[130:131], v[132:133]
	v_pk_mul_f32 v[122:123], v[122:123], v[200:201] op_sel_hi:[1,0]
	v_mul_f32_e32 v147, 0x45800000, v146
	v_mul_f32_e32 v140, 0x45800000, v139
	v_pk_fma_f32 v[130:131], v[130:131], s[22:23], v[202:203] op_sel_hi:[1,0,0]
	v_cndmask_b32_e32 v146, v146, v147, vcc
	v_cmp_gt_f32_e32 vcc, s39, v138
	v_cndmask_b32_e64 v140, v139, v140, s[42:43]
	v_mul_f32_e32 v139, 0x4b800000, v138
	v_mul_f32_e32 v132, 0x4b800000, v131
	v_cmp_gt_f32_e64 s[42:43], s39, v131
	v_cndmask_b32_e32 v138, v138, v139, vcc
	v_rsq_f32_e32 v138, v138
	v_cndmask_b32_e64 v131, v131, v132, s[42:43]
	v_rsq_f32_e32 v131, v131
	v_pk_mul_f32 v[124:125], v[124:125], v[200:201] op_sel_hi:[1,0]
	v_mul_f32_e32 v139, 0x45800000, v138
	v_cndmask_b32_e32 v138, v138, v139, vcc
	v_mul_f32_e32 v132, 0x45800000, v131
	v_cmp_gt_f32_e32 vcc, s39, v130
	v_cndmask_b32_e64 v132, v131, v132, s[42:43]
	v_mul_f32_e32 v131, 0x4b800000, v130
	v_cndmask_b32_e32 v130, v130, v131, vcc
	v_rsq_f32_e32 v130, v130
	v_pk_mul_f32 v[118:119], v[118:119], v[200:201] op_sel_hi:[1,0]
	v_pk_mul_f32 v[114:115], v[114:115], v[200:201] op_sel_hi:[1,0]
	v_lshl_or_b32 v134, s34, 7, v204
	v_mul_f32_e32 v131, 0x45800000, v130
	v_cndmask_b32_e32 v130, v130, v131, vcc
	v_mul_f32_e32 v131, 0xbfb8aa3b, v126
	v_exp_f32_e32 v131, v131
	v_pk_mul_f32 v[116:117], v[116:117], v[200:201] op_sel_hi:[1,0]
	v_ashrrev_i32_e32 v135, 31, v134
	v_pk_mul_f32 v[110:111], v[110:111], v[198:199] op_sel_hi:[1,0]
	v_add_f32_e32 v131, 1.0, v131
	v_rcp_f32_e32 v136, v131
	v_mul_f32_e32 v131, 0xbfb8aa3b, v127
	v_exp_f32_e32 v131, v131
	v_pk_mul_f32 v[106:107], v[106:107], v[198:199] op_sel_hi:[1,0]
	v_pk_mul_f32 v[108:109], v[108:109], v[198:199] op_sel_hi:[1,0]
	v_pk_mul_f32 v[102:103], v[102:103], v[198:199] op_sel_hi:[1,0]
	v_add_f32_e32 v131, 1.0, v131
	v_rcp_f32_e32 v137, v131
	v_pk_mul_f32 v[98:99], v[98:99], v[198:199] op_sel_hi:[1,0]
	v_pk_mul_f32 v[100:101], v[100:101], v[198:199] op_sel_hi:[1,0]
	v_pk_mul_f32 v[94:95], v[94:95], v[148:149] op_sel_hi:[1,0]
	v_pk_mul_f32 v[126:127], v[126:127], v[136:137]
	v_pk_mul_f32 v[90:91], v[90:91], v[148:149] op_sel_hi:[1,0]
	v_pk_mul_f32 v[122:123], v[122:123], v[126:127]
	v_pk_mul_f32 v[126:127], v[128:129], v[200:201] op_sel_hi:[1,0]
	v_cvt_pk_bf16_f32 v122, v122, v123
	v_mul_f32_e32 v128, 0xbfb8aa3b, v126
	v_mul_f32_e32 v129, 0xbfb8aa3b, v127
	v_exp_f32_e32 v128, v128
	v_exp_f32_e32 v129, v129
	v_pk_mul_f32 v[92:93], v[92:93], v[148:149] op_sel_hi:[1,0]
	v_pk_mul_f32 v[86:87], v[86:87], v[148:149] op_sel_hi:[1,0]
	v_add_f32_e32 v128, 1.0, v128
	v_add_f32_e32 v129, 1.0, v129
	v_rcp_f32_e32 v128, v128
	v_rcp_f32_e32 v129, v129
	v_pk_mul_f32 v[82:83], v[82:83], v[148:149] op_sel_hi:[1,0]
	v_pk_mul_f32 v[84:85], v[84:85], v[148:149] op_sel_hi:[1,0]
	v_pk_mul_f32 v[78:79], v[78:79], v[146:147] op_sel_hi:[1,0]
	v_pk_mul_f32 v[126:127], v[126:127], v[128:129]
	v_pk_mul_f32 v[74:75], v[74:75], v[146:147] op_sel_hi:[1,0]
	v_pk_mul_f32 v[124:125], v[124:125], v[126:127]
	v_pk_mul_f32 v[76:77], v[76:77], v[146:147] op_sel_hi:[1,0]
	v_cvt_pk_bf16_f32 v123, v124, v125
	v_mul_f32_e32 v124, 0xbfb8aa3b, v118
	v_mul_f32_e32 v125, 0xbfb8aa3b, v119
	v_exp_f32_e32 v124, v124
	v_exp_f32_e32 v125, v125
	v_pk_mul_f32 v[70:71], v[70:71], v[146:147] op_sel_hi:[1,0]
	v_pk_mul_f32 v[66:67], v[66:67], v[146:147] op_sel_hi:[1,0]
	v_add_f32_e32 v124, 1.0, v124
	v_add_f32_e32 v125, 1.0, v125
	v_rcp_f32_e32 v124, v124
	v_rcp_f32_e32 v125, v125
	v_pk_mul_f32 v[68:69], v[68:69], v[146:147] op_sel_hi:[1,0]
	v_pk_mul_f32 v[62:63], v[62:63], v[140:141] op_sel_hi:[1,0]
	v_pk_mul_f32 v[58:59], v[58:59], v[140:141] op_sel_hi:[1,0]
	v_pk_mul_f32 v[118:119], v[118:119], v[124:125]
	v_pk_mul_f32 v[60:61], v[60:61], v[140:141] op_sel_hi:[1,0]
	v_pk_mul_f32 v[114:115], v[114:115], v[118:119]
	v_pk_mul_f32 v[118:119], v[120:121], v[200:201] op_sel_hi:[1,0]
	v_cvt_pk_bf16_f32 v124, v114, v115
	v_mul_f32_e32 v120, 0xbfb8aa3b, v118
	v_mul_f32_e32 v121, 0xbfb8aa3b, v119
	v_exp_f32_e32 v120, v120
	v_exp_f32_e32 v121, v121
	v_mov_b64_e32 v[114:115], s[68:69]
	v_pk_mul_f32 v[54:55], v[54:55], v[140:141] op_sel_hi:[1,0]
	v_add_f32_e32 v120, 1.0, v120
	v_add_f32_e32 v121, 1.0, v121
	v_rcp_f32_e32 v120, v120
	v_rcp_f32_e32 v121, v121
	v_pk_mul_f32 v[50:51], v[50:51], v[140:141] op_sel_hi:[1,0]
	v_pk_mul_f32 v[52:53], v[52:53], v[140:141] op_sel_hi:[1,0]
	v_pk_mul_f32 v[46:47], v[46:47], v[138:139] op_sel_hi:[1,0]
	v_pk_mul_f32 v[118:119], v[118:119], v[120:121]
	v_pk_mul_f32 v[42:43], v[42:43], v[138:139] op_sel_hi:[1,0]
	v_pk_mul_f32 v[116:117], v[116:117], v[118:119]
	v_mad_i64_i32 v[118:119], s[22:23], v196, s38, v[114:115]
	v_cvt_pk_bf16_f32 v125, v116, v117
	v_lshlrev_b64 v[116:117], 1, v[134:135]
	v_lshl_add_u64 v[118:119], v[118:119], 0, v[116:117]
	global_store_dwordx4 v[118:119], v[122:125], off
	v_mul_f32_e32 v118, 0xbfb8aa3b, v110
	v_mul_f32_e32 v119, 0xbfb8aa3b, v111
	v_exp_f32_e32 v118, v118
	v_exp_f32_e32 v119, v119
	v_pk_mul_f32 v[44:45], v[44:45], v[138:139] op_sel_hi:[1,0]
	v_pk_mul_f32 v[38:39], v[38:39], v[138:139] op_sel_hi:[1,0]
	v_add_f32_e32 v118, 1.0, v118
	v_add_f32_e32 v119, 1.0, v119
	v_rcp_f32_e32 v118, v118
	v_rcp_f32_e32 v119, v119
	v_pk_mul_f32 v[34:35], v[34:35], v[138:139] op_sel_hi:[1,0]
	v_pk_mul_f32 v[36:37], v[36:37], v[138:139] op_sel_hi:[1,0]
	v_pk_mul_f32 v[30:31], v[30:31], v[132:133] op_sel_hi:[1,0]
	v_pk_mul_f32 v[110:111], v[110:111], v[118:119]
	v_pk_mul_f32 v[26:27], v[26:27], v[132:133] op_sel_hi:[1,0]
	v_pk_mul_f32 v[106:107], v[106:107], v[110:111]
	v_pk_mul_f32 v[110:111], v[112:113], v[198:199] op_sel_hi:[1,0]
	v_cvt_pk_bf16_f32 v106, v106, v107
	v_mul_f32_e32 v112, 0xbfb8aa3b, v110
	v_mul_f32_e32 v113, 0xbfb8aa3b, v111
	v_exp_f32_e32 v112, v112
	v_exp_f32_e32 v113, v113
	v_pk_mul_f32 v[28:29], v[28:29], v[132:133] op_sel_hi:[1,0]
	v_pk_mul_f32 v[22:23], v[22:23], v[132:133] op_sel_hi:[1,0]
	v_add_f32_e32 v112, 1.0, v112
	v_add_f32_e32 v113, 1.0, v113
	v_rcp_f32_e32 v112, v112
	v_rcp_f32_e32 v113, v113
	v_pk_mul_f32 v[18:19], v[18:19], v[132:133] op_sel_hi:[1,0]
	v_pk_mul_f32 v[20:21], v[20:21], v[132:133] op_sel_hi:[1,0]
	v_pk_mul_f32 v[14:15], v[14:15], v[130:131] op_sel_hi:[1,0]
	v_pk_mul_f32 v[110:111], v[110:111], v[112:113]
	v_pk_mul_f32 v[10:11], v[10:11], v[130:131] op_sel_hi:[1,0]
	v_pk_mul_f32 v[108:109], v[108:109], v[110:111]
	v_pk_mul_f32 v[12:13], v[12:13], v[130:131] op_sel_hi:[1,0]
	v_cvt_pk_bf16_f32 v107, v108, v109
	v_mul_f32_e32 v108, 0xbfb8aa3b, v102
	v_mul_f32_e32 v109, 0xbfb8aa3b, v103
	v_exp_f32_e32 v108, v108
	v_exp_f32_e32 v109, v109
	v_pk_mul_f32 v[6:7], v[6:7], v[130:131] op_sel_hi:[1,0]
	v_pk_mul_f32 v[2:3], v[2:3], v[130:131] op_sel_hi:[1,0]
	v_add_f32_e32 v108, 1.0, v108
	v_add_f32_e32 v109, 1.0, v109
	v_rcp_f32_e32 v108, v108
	v_rcp_f32_e32 v109, v109
	v_pk_mul_f32 v[4:5], v[4:5], v[130:131] op_sel_hi:[1,0]
	s_and_b64 vcc, exec, s[40:41]
	s_mov_b32 s34, s6
	v_pk_mul_f32 v[102:103], v[102:103], v[108:109]
	s_nop 0
	v_pk_mul_f32 v[98:99], v[98:99], v[102:103]
	v_pk_mul_f32 v[102:103], v[104:105], v[198:199] op_sel_hi:[1,0]
	v_cvt_pk_bf16_f32 v108, v98, v99
	v_mul_f32_e32 v104, 0xbfb8aa3b, v102
	v_mul_f32_e32 v105, 0xbfb8aa3b, v103
	v_exp_f32_e32 v104, v104
	v_exp_f32_e32 v105, v105
	v_mad_i64_i32 v[98:99], s[22:23], v194, s38, v[114:115]
	v_add_f32_e32 v104, 1.0, v104
	v_add_f32_e32 v105, 1.0, v105
	v_rcp_f32_e32 v104, v104
	v_rcp_f32_e32 v105, v105
	v_lshl_add_u64 v[98:99], v[98:99], 0, v[116:117]
	v_pk_mul_f32 v[102:103], v[102:103], v[104:105]
	s_nop 0
	v_pk_mul_f32 v[100:101], v[100:101], v[102:103]
	s_nop 0
	v_cvt_pk_bf16_f32 v109, v100, v101
	global_store_dwordx4 v[98:99], v[106:109], off
	v_mul_f32_e32 v98, 0xbfb8aa3b, v94
	v_mul_f32_e32 v99, 0xbfb8aa3b, v95
	v_exp_f32_e32 v98, v98
	v_exp_f32_e32 v99, v99
	v_add_f32_e32 v98, 1.0, v98
	v_add_f32_e32 v99, 1.0, v99
	v_rcp_f32_e32 v98, v98
	v_rcp_f32_e32 v99, v99
	s_nop 0
	v_pk_mul_f32 v[94:95], v[94:95], v[98:99]
	s_nop 0
	v_pk_mul_f32 v[90:91], v[90:91], v[94:95]
	v_pk_mul_f32 v[94:95], v[96:97], v[148:149] op_sel_hi:[1,0]
	v_cvt_pk_bf16_f32 v90, v90, v91
	v_mul_f32_e32 v96, 0xbfb8aa3b, v94
	v_mul_f32_e32 v97, 0xbfb8aa3b, v95
	v_exp_f32_e32 v96, v96
	v_exp_f32_e32 v97, v97
	v_add_f32_e32 v96, 1.0, v96
	v_add_f32_e32 v97, 1.0, v97
	v_rcp_f32_e32 v96, v96
	v_rcp_f32_e32 v97, v97
	s_nop 0
	v_pk_mul_f32 v[94:95], v[94:95], v[96:97]
	s_nop 0
	v_pk_mul_f32 v[92:93], v[92:93], v[94:95]
	s_nop 0
	v_cvt_pk_bf16_f32 v91, v92, v93
	v_mul_f32_e32 v92, 0xbfb8aa3b, v86
	v_mul_f32_e32 v93, 0xbfb8aa3b, v87
	v_exp_f32_e32 v92, v92
	v_exp_f32_e32 v93, v93
	v_add_f32_e32 v92, 1.0, v92
	v_add_f32_e32 v93, 1.0, v93
	v_rcp_f32_e32 v92, v92
	v_rcp_f32_e32 v93, v93
	s_nop 0
	v_pk_mul_f32 v[86:87], v[86:87], v[92:93]
	s_nop 0
	v_pk_mul_f32 v[82:83], v[82:83], v[86:87]
	v_pk_mul_f32 v[86:87], v[88:89], v[148:149] op_sel_hi:[1,0]
	v_cvt_pk_bf16_f32 v92, v82, v83
	v_mul_f32_e32 v88, 0xbfb8aa3b, v86
	v_mul_f32_e32 v89, 0xbfb8aa3b, v87
	v_exp_f32_e32 v88, v88
	v_exp_f32_e32 v89, v89
	v_mad_i64_i32 v[82:83], s[22:23], v192, s38, v[114:115]
	v_add_f32_e32 v88, 1.0, v88
	v_add_f32_e32 v89, 1.0, v89
	v_rcp_f32_e32 v88, v88
	v_rcp_f32_e32 v89, v89
	v_lshl_add_u64 v[82:83], v[82:83], 0, v[116:117]
	v_pk_mul_f32 v[86:87], v[86:87], v[88:89]
	s_nop 0
	v_pk_mul_f32 v[84:85], v[84:85], v[86:87]
	s_nop 0
	v_cvt_pk_bf16_f32 v93, v84, v85
	global_store_dwordx4 v[82:83], v[90:93], off
	v_mul_f32_e32 v82, 0xbfb8aa3b, v78
	v_mul_f32_e32 v83, 0xbfb8aa3b, v79
	v_exp_f32_e32 v82, v82
	v_exp_f32_e32 v83, v83
	v_add_f32_e32 v82, 1.0, v82
	v_add_f32_e32 v83, 1.0, v83
	v_rcp_f32_e32 v82, v82
	v_rcp_f32_e32 v83, v83
	s_nop 0
	v_pk_mul_f32 v[78:79], v[78:79], v[82:83]
	s_nop 0
	v_pk_mul_f32 v[74:75], v[74:75], v[78:79]
	v_pk_mul_f32 v[78:79], v[80:81], v[146:147] op_sel_hi:[1,0]
	v_cvt_pk_bf16_f32 v74, v74, v75
	v_mul_f32_e32 v80, 0xbfb8aa3b, v78
	v_mul_f32_e32 v81, 0xbfb8aa3b, v79
	v_exp_f32_e32 v80, v80
	v_exp_f32_e32 v81, v81
	v_add_f32_e32 v80, 1.0, v80
	v_add_f32_e32 v81, 1.0, v81
	v_rcp_f32_e32 v80, v80
	v_rcp_f32_e32 v81, v81
	s_nop 0
	v_pk_mul_f32 v[78:79], v[78:79], v[80:81]
	s_nop 0
	v_pk_mul_f32 v[76:77], v[76:77], v[78:79]
	s_nop 0
	v_cvt_pk_bf16_f32 v75, v76, v77
	v_mul_f32_e32 v76, 0xbfb8aa3b, v70
	v_mul_f32_e32 v77, 0xbfb8aa3b, v71
	v_exp_f32_e32 v76, v76
	v_exp_f32_e32 v77, v77
	v_add_f32_e32 v76, 1.0, v76
	v_add_f32_e32 v77, 1.0, v77
	v_rcp_f32_e32 v76, v76
	v_rcp_f32_e32 v77, v77
	s_nop 0
	v_pk_mul_f32 v[70:71], v[70:71], v[76:77]
	s_nop 0
	v_pk_mul_f32 v[66:67], v[66:67], v[70:71]
	v_pk_mul_f32 v[70:71], v[72:73], v[146:147] op_sel_hi:[1,0]
	v_cvt_pk_bf16_f32 v76, v66, v67
	v_mul_f32_e32 v72, 0xbfb8aa3b, v70
	v_mul_f32_e32 v73, 0xbfb8aa3b, v71
	v_exp_f32_e32 v72, v72
	v_exp_f32_e32 v73, v73
	v_mad_i64_i32 v[66:67], s[22:23], v190, s38, v[114:115]
	v_add_f32_e32 v72, 1.0, v72
	v_add_f32_e32 v73, 1.0, v73
	v_rcp_f32_e32 v72, v72
	v_rcp_f32_e32 v73, v73
	v_lshl_add_u64 v[66:67], v[66:67], 0, v[116:117]
	v_pk_mul_f32 v[70:71], v[70:71], v[72:73]
	s_nop 0
	v_pk_mul_f32 v[68:69], v[68:69], v[70:71]
	s_nop 0
	v_cvt_pk_bf16_f32 v77, v68, v69
	global_store_dwordx4 v[66:67], v[74:77], off
	v_mul_f32_e32 v66, 0xbfb8aa3b, v62
	v_mul_f32_e32 v67, 0xbfb8aa3b, v63
	v_exp_f32_e32 v66, v66
	v_exp_f32_e32 v67, v67
	v_add_f32_e32 v66, 1.0, v66
	v_add_f32_e32 v67, 1.0, v67
	v_rcp_f32_e32 v66, v66
	v_rcp_f32_e32 v67, v67
	s_nop 0
	v_pk_mul_f32 v[62:63], v[62:63], v[66:67]
	s_nop 0
	v_pk_mul_f32 v[58:59], v[58:59], v[62:63]
	v_pk_mul_f32 v[62:63], v[64:65], v[140:141] op_sel_hi:[1,0]
	v_cvt_pk_bf16_f32 v58, v58, v59
	v_mul_f32_e32 v64, 0xbfb8aa3b, v62
	v_mul_f32_e32 v65, 0xbfb8aa3b, v63
	v_exp_f32_e32 v64, v64
	v_exp_f32_e32 v65, v65
	v_add_f32_e32 v64, 1.0, v64
	v_add_f32_e32 v65, 1.0, v65
	v_rcp_f32_e32 v64, v64
	v_rcp_f32_e32 v65, v65
	s_nop 0
	v_pk_mul_f32 v[62:63], v[62:63], v[64:65]
	s_nop 0
	v_pk_mul_f32 v[60:61], v[60:61], v[62:63]
	s_nop 0
	v_cvt_pk_bf16_f32 v59, v60, v61
	v_mul_f32_e32 v60, 0xbfb8aa3b, v54
	v_mul_f32_e32 v61, 0xbfb8aa3b, v55
	v_exp_f32_e32 v60, v60
	v_exp_f32_e32 v61, v61
	v_add_f32_e32 v60, 1.0, v60
	v_add_f32_e32 v61, 1.0, v61
	v_rcp_f32_e32 v60, v60
	v_rcp_f32_e32 v61, v61
	s_nop 0
	v_pk_mul_f32 v[54:55], v[54:55], v[60:61]
	s_nop 0
	v_pk_mul_f32 v[50:51], v[50:51], v[54:55]
	v_pk_mul_f32 v[54:55], v[56:57], v[140:141] op_sel_hi:[1,0]
	v_cvt_pk_bf16_f32 v60, v50, v51
	v_mul_f32_e32 v56, 0xbfb8aa3b, v54
	v_mul_f32_e32 v57, 0xbfb8aa3b, v55
	v_exp_f32_e32 v56, v56
	v_exp_f32_e32 v57, v57
	v_mad_i64_i32 v[50:51], s[22:23], v188, s38, v[114:115]
	v_add_f32_e32 v56, 1.0, v56
	v_add_f32_e32 v57, 1.0, v57
	v_rcp_f32_e32 v56, v56
	v_rcp_f32_e32 v57, v57
	v_lshl_add_u64 v[50:51], v[50:51], 0, v[116:117]
	v_pk_mul_f32 v[54:55], v[54:55], v[56:57]
	s_nop 0
	v_pk_mul_f32 v[52:53], v[52:53], v[54:55]
	s_nop 0
	v_cvt_pk_bf16_f32 v61, v52, v53
	global_store_dwordx4 v[50:51], v[58:61], off
	v_mul_f32_e32 v50, 0xbfb8aa3b, v46
	v_mul_f32_e32 v51, 0xbfb8aa3b, v47
	v_exp_f32_e32 v50, v50
	v_exp_f32_e32 v51, v51
	v_add_f32_e32 v50, 1.0, v50
	v_add_f32_e32 v51, 1.0, v51
	v_rcp_f32_e32 v50, v50
	v_rcp_f32_e32 v51, v51
	s_nop 0
	v_pk_mul_f32 v[46:47], v[46:47], v[50:51]
	s_nop 0
	v_pk_mul_f32 v[42:43], v[42:43], v[46:47]
	v_pk_mul_f32 v[46:47], v[48:49], v[138:139] op_sel_hi:[1,0]
	v_cvt_pk_bf16_f32 v42, v42, v43
	v_mul_f32_e32 v48, 0xbfb8aa3b, v46
	v_mul_f32_e32 v49, 0xbfb8aa3b, v47
	v_exp_f32_e32 v48, v48
	v_exp_f32_e32 v49, v49
	v_add_f32_e32 v48, 1.0, v48
	v_add_f32_e32 v49, 1.0, v49
	v_rcp_f32_e32 v48, v48
	v_rcp_f32_e32 v49, v49
	s_nop 0
	v_pk_mul_f32 v[46:47], v[46:47], v[48:49]
	s_nop 0
	v_pk_mul_f32 v[44:45], v[44:45], v[46:47]
	s_nop 0
	v_cvt_pk_bf16_f32 v43, v44, v45
	v_mul_f32_e32 v44, 0xbfb8aa3b, v38
	v_mul_f32_e32 v45, 0xbfb8aa3b, v39
	v_exp_f32_e32 v44, v44
	v_exp_f32_e32 v45, v45
	v_add_f32_e32 v44, 1.0, v44
	v_add_f32_e32 v45, 1.0, v45
	v_rcp_f32_e32 v44, v44
	v_rcp_f32_e32 v45, v45
	s_nop 0
	v_pk_mul_f32 v[38:39], v[38:39], v[44:45]
	s_nop 0
	v_pk_mul_f32 v[34:35], v[34:35], v[38:39]
	v_pk_mul_f32 v[38:39], v[40:41], v[138:139] op_sel_hi:[1,0]
	v_cvt_pk_bf16_f32 v44, v34, v35
	v_mul_f32_e32 v40, 0xbfb8aa3b, v38
	v_mul_f32_e32 v41, 0xbfb8aa3b, v39
	v_exp_f32_e32 v40, v40
	v_exp_f32_e32 v41, v41
	v_mad_i64_i32 v[34:35], s[22:23], v186, s38, v[114:115]
	v_add_f32_e32 v40, 1.0, v40
	v_add_f32_e32 v41, 1.0, v41
	v_rcp_f32_e32 v40, v40
	v_rcp_f32_e32 v41, v41
	v_lshl_add_u64 v[34:35], v[34:35], 0, v[116:117]
	v_pk_mul_f32 v[38:39], v[38:39], v[40:41]
	s_nop 0
	v_pk_mul_f32 v[36:37], v[36:37], v[38:39]
	s_nop 0
	v_cvt_pk_bf16_f32 v45, v36, v37
	global_store_dwordx4 v[34:35], v[42:45], off
	v_mul_f32_e32 v34, 0xbfb8aa3b, v30
	v_mul_f32_e32 v35, 0xbfb8aa3b, v31
	v_exp_f32_e32 v34, v34
	v_exp_f32_e32 v35, v35
	v_add_f32_e32 v34, 1.0, v34
	v_add_f32_e32 v35, 1.0, v35
	v_rcp_f32_e32 v34, v34
	v_rcp_f32_e32 v35, v35
	s_nop 0
	v_pk_mul_f32 v[30:31], v[30:31], v[34:35]
	s_nop 0
	v_pk_mul_f32 v[26:27], v[26:27], v[30:31]
	v_pk_mul_f32 v[30:31], v[32:33], v[132:133] op_sel_hi:[1,0]
	v_cvt_pk_bf16_f32 v26, v26, v27
	v_mul_f32_e32 v32, 0xbfb8aa3b, v30
	v_mul_f32_e32 v33, 0xbfb8aa3b, v31
	v_exp_f32_e32 v32, v32
	v_exp_f32_e32 v33, v33
	v_add_f32_e32 v32, 1.0, v32
	v_add_f32_e32 v33, 1.0, v33
	v_rcp_f32_e32 v32, v32
	v_rcp_f32_e32 v33, v33
	s_nop 0
	v_pk_mul_f32 v[30:31], v[30:31], v[32:33]
	s_nop 0
	v_pk_mul_f32 v[28:29], v[28:29], v[30:31]
	s_nop 0
	v_cvt_pk_bf16_f32 v27, v28, v29
	v_mul_f32_e32 v28, 0xbfb8aa3b, v22
	v_mul_f32_e32 v29, 0xbfb8aa3b, v23
	v_exp_f32_e32 v28, v28
	v_exp_f32_e32 v29, v29
	v_add_f32_e32 v28, 1.0, v28
	v_add_f32_e32 v29, 1.0, v29
	v_rcp_f32_e32 v28, v28
	v_rcp_f32_e32 v29, v29
	s_nop 0
	v_pk_mul_f32 v[22:23], v[22:23], v[28:29]
	s_nop 0
	v_pk_mul_f32 v[18:19], v[18:19], v[22:23]
	v_pk_mul_f32 v[22:23], v[24:25], v[132:133] op_sel_hi:[1,0]
	v_cvt_pk_bf16_f32 v28, v18, v19
	v_mul_f32_e32 v24, 0xbfb8aa3b, v22
	v_mul_f32_e32 v25, 0xbfb8aa3b, v23
	v_exp_f32_e32 v24, v24
	v_exp_f32_e32 v25, v25
	v_mad_i64_i32 v[18:19], s[22:23], v184, s38, v[114:115]
	v_add_f32_e32 v24, 1.0, v24
	v_add_f32_e32 v25, 1.0, v25
	v_rcp_f32_e32 v24, v24
	v_rcp_f32_e32 v25, v25
	v_lshl_add_u64 v[18:19], v[18:19], 0, v[116:117]
	v_pk_mul_f32 v[22:23], v[22:23], v[24:25]
	s_nop 0
	v_pk_mul_f32 v[20:21], v[20:21], v[22:23]
	s_nop 0
	v_cvt_pk_bf16_f32 v29, v20, v21
	global_store_dwordx4 v[18:19], v[26:29], off
	v_mul_f32_e32 v18, 0xbfb8aa3b, v14
	v_mul_f32_e32 v19, 0xbfb8aa3b, v15
	v_exp_f32_e32 v18, v18
	v_exp_f32_e32 v19, v19
	v_add_f32_e32 v18, 1.0, v18
	v_add_f32_e32 v19, 1.0, v19
	v_rcp_f32_e32 v18, v18
	v_rcp_f32_e32 v19, v19
	s_nop 0
	v_pk_mul_f32 v[14:15], v[14:15], v[18:19]
	s_nop 0
	v_pk_mul_f32 v[10:11], v[10:11], v[14:15]
	v_pk_mul_f32 v[14:15], v[16:17], v[130:131] op_sel_hi:[1,0]
	v_cvt_pk_bf16_f32 v10, v10, v11
	v_mul_f32_e32 v16, 0xbfb8aa3b, v14
	v_mul_f32_e32 v17, 0xbfb8aa3b, v15
	v_exp_f32_e32 v16, v16
	v_exp_f32_e32 v17, v17
	v_add_f32_e32 v16, 1.0, v16
	v_add_f32_e32 v17, 1.0, v17
	v_rcp_f32_e32 v16, v16
	v_rcp_f32_e32 v17, v17
	s_nop 0
	v_pk_mul_f32 v[14:15], v[14:15], v[16:17]
	s_nop 0
	v_pk_mul_f32 v[12:13], v[12:13], v[14:15]
	s_nop 0
	v_cvt_pk_bf16_f32 v11, v12, v13
	v_mul_f32_e32 v12, 0xbfb8aa3b, v6
	v_mul_f32_e32 v13, 0xbfb8aa3b, v7
	v_exp_f32_e32 v12, v12
	v_exp_f32_e32 v13, v13
	v_add_f32_e32 v12, 1.0, v12
	v_add_f32_e32 v13, 1.0, v13
	v_rcp_f32_e32 v12, v12
	v_rcp_f32_e32 v13, v13
	s_nop 0
	v_pk_mul_f32 v[6:7], v[6:7], v[12:13]
	s_nop 0
	v_pk_mul_f32 v[2:3], v[2:3], v[6:7]
	v_pk_mul_f32 v[6:7], v[8:9], v[130:131] op_sel_hi:[1,0]
	v_cvt_pk_bf16_f32 v12, v2, v3
	v_mul_f32_e32 v8, 0xbfb8aa3b, v6
	v_mul_f32_e32 v9, 0xbfb8aa3b, v7
	v_exp_f32_e32 v8, v8
	v_exp_f32_e32 v9, v9
	v_mad_i64_i32 v[2:3], s[22:23], v182, s38, v[114:115]
	v_add_f32_e32 v8, 1.0, v8
	v_add_f32_e32 v9, 1.0, v9
	v_rcp_f32_e32 v8, v8
	v_rcp_f32_e32 v9, v9
	v_lshl_add_u64 v[2:3], v[2:3], 0, v[116:117]
	v_pk_mul_f32 v[6:7], v[6:7], v[8:9]
	s_nop 0
	v_pk_mul_f32 v[4:5], v[4:5], v[6:7]
	s_nop 0
	v_cvt_pk_bf16_f32 v13, v4, v5
	global_store_dwordx4 v[2:3], v[10:13], off
	s_cbranch_vccz .LBB0_80
	s_waitcnt vmcnt(0)
	s_cmpk_gt_u32 s0, 0xff
	s_cbranch_scc1 .LBB0_87
	s_barrier

	.amdhsa_kernel _Z10fwd_kernel6Params
		.amdhsa_group_segment_fixed_size 0
		.amdhsa_private_segment_fixed_size 0
		.amdhsa_kernarg_size 496
		.amdhsa_user_sgpr_count 2
		.amdhsa_user_sgpr_dispatch_ptr 0
		.amdhsa_user_sgpr_queue_ptr 0
		.amdhsa_user_sgpr_kernarg_segment_ptr 1
		.amdhsa_user_sgpr_dispatch_id 0
		.amdhsa_user_sgpr_kernarg_preload_length 0
		.amdhsa_user_sgpr_kernarg_preload_offset 0
		.amdhsa_user_sgpr_private_segment_size 0
		.amdhsa_uses_dynamic_stack 0
		.amdhsa_enable_private_segment 0
		.amdhsa_system_sgpr_workgroup_id_x 1
		.amdhsa_system_sgpr_workgroup_id_y 0
		.amdhsa_system_sgpr_workgroup_id_z 0
		.amdhsa_system_sgpr_workgroup_info 0
		.amdhsa_system_vgpr_workitem_id 2
		.amdhsa_next_free_vgpr 256
		.amdhsa_next_free_sgpr 102
		.amdhsa_accum_offset 256
		.amdhsa_reserve_vcc 1
		.amdhsa_float_round_mode_32 0
		.amdhsa_float_round_mode_16_64 0
		.amdhsa_float_denorm_mode_32 3
		.amdhsa_float_denorm_mode_16_64 3
		.amdhsa_dx10_clamp 1
		.amdhsa_ieee_mode 1
		.amdhsa_fp16_overflow 0
		.amdhsa_tg_split 0
		.amdhsa_exception_fp_ieee_invalid_op 0
		.amdhsa_exception_fp_denorm_src 0
		.amdhsa_exception_fp_ieee_div_zero 0
		.amdhsa_exception_fp_ieee_overflow 0
		.amdhsa_exception_fp_ieee_underflow 0
		.amdhsa_exception_fp_ieee_inexact 0
		.amdhsa_exception_int_div_zero 0
	.end_amdhsa_kernel

amdhsa.kernels:
  - .agpr_count:     0
    .args:
      - .offset:         0
        .size:           240
        .value_kind:     by_value
      - .offset:         240
        .size:           4
        .value_kind:     hidden_block_count_x
      - .offset:         244
        .size:           4
        .value_kind:     hidden_block_count_y
      - .offset:         248
        .size:           4
        .value_kind:     hidden_block_count_z
      - .offset:         252
        .size:           2
        .value_kind:     hidden_group_size_x
      - .offset:         254
        .size:           2
        .value_kind:     hidden_group_size_y
      - .offset:         256
        .size:           2
        .value_kind:     hidden_group_size_z
      - .offset:         258
        .size:           2
        .value_kind:     hidden_remainder_x
      - .offset:         260
        .size:           2
        .value_kind:     hidden_remainder_y
      - .offset:         262
        .size:           2
        .value_kind:     hidden_remainder_z
      - .offset:         280
        .size:           8
        .value_kind:     hidden_global_offset_x
      - .offset:         288
        .size:           8
        .value_kind:     hidden_global_offset_y
      - .offset:         296
        .size:           8
        .value_kind:     hidden_global_offset_z
      - .offset:         304
        .size:           2
        .value_kind:     hidden_grid_dims
      - .offset:         328
        .size:           8
        .value_kind:     hidden_multigrid_sync_arg
      - .offset:         360
        .size:           4
        .value_kind:     hidden_dynamic_lds_size
    .group_segment_fixed_size: 0
    .kernarg_segment_align: 8
    .kernarg_segment_size: 496
    .language:       OpenCL C
    .language_version:
      - 2
      - 0
    .max_flat_workgroup_size: 512
    .name:           _Z10fwd_kernel6Params
    .private_segment_fixed_size: 0
    .sgpr_count:     108
    .sgpr_spill_count: 196
    .symbol:         _Z10fwd_kernel6Params.kd
    .uniform_work_group_size: 1
    .uses_dynamic_stack: false
    .vgpr_count:     256
    .vgpr_spill_count: 0
    .wavefront_size: 64
